# v28: v26 + the per-call L1 invalidate of kinds 3, 6, 7 is issued by wave 1 in parallel with wave 0's dependency poll (nothing loads the dependent panels before the barrier that follows the poll)
# speedup vs baseline: 1.0052x; 1.0024x over previous
.LBB0_322:
	s_cmp_gt_i32 s42, 2
	s_mov_b64 s[12:13], -1
	s_cbranch_scc0 .LBB0_328
	s_cmp_eq_u32 s42, 3
	s_mov_b64 s[8:9], -1
	s_cbranch_scc0 .LBB0_339
	s_mov_b64 s[8:9], s[0:1]
	s_mov_b64 s[66:67], s[0:1]
	s_mov_b64 s[12:13], s[0:1]
	s_mov_b64 s[70:71], s[0:1]
	s_waitcnt vmcnt(27)
	v_mov_b32_e32 v6, v0
	s_add_i32 s6, s36, 0xffffff28
	s_cmpk_gt_i32 s6, 0x47
	v_readfirstlane_b32 s29, v6
	s_mov_b32 s57, 0
	s_cbranch_scc1 .LBB0_419
	v_bfe_i32 v4, v6, 27, 1
	v_lshlrev_b32_e32 v2, 4, v6
	v_lshrrev_b32_e32 v4, 22, v4
	v_add_u32_e32 v4, v2, v4
	v_and_b32_e32 v4, 0xfffffc00, v4
	v_sub_u32_e32 v4, v2, v4
	v_ashrrev_i32_e32 v1, 31, v6
	s_waitcnt vmcnt(26)
	v_lshrrev_b32_e32 v5, 4, v4
	v_lshrrev_b32_e32 v1, 26, v1
	v_bitop3_b32 v4, v5, v4, 32 bitop3:0x6c
	v_add_u32_e32 v1, v6, v1
	s_waitcnt vmcnt(24)
	v_ashrrev_i32_e32 v7, 31, v4
	v_ashrrev_i32_e32 v1, 6, v1
	v_lshrrev_b32_e32 v7, 26, v7
	v_lshlrev_b32_e32 v5, 3, v1
	v_add_u32_e32 v8, v4, v7
	v_and_b32_e32 v5, -16, v5
	s_waitcnt vmcnt(22)
	v_ashrrev_i32_e32 v9, 6, v8
	v_add_u32_e32 v7, v9, v5
	v_and_b32_e32 v5, 0xc0, v8
	v_sub_u32_e32 v4, v4, v5
	v_lshlrev_b32_e32 v1, 5, v1
	v_ashrrev_i16_sdwa v4, v253, sext(v4) dst_sel:DWORD dst_unused:UNUSED_PAD src0_sel:DWORD src1_sel:BYTE_0
	v_lshlrev_b32_e32 v5, 1, v7
	v_lshrrev_b32_e32 v8, 2, v7
	v_and_b32_e32 v9, 3, v9
	s_mov_b32 s7, 0x1fffe0
	v_and_b32_e32 v1, 32, v1
	v_bfe_i32 v4, v4, 0, 16
	v_and_b32_e32 v5, 24, v5
	v_and_b32_e32 v8, 4, v8
	v_and_or_b32 v9, v7, s7, v9
	v_add_u32_e32 v2, 0x2000, v2
	v_or3_b32 v5, v9, v8, v5
	v_add_lshl_u32 v8, v1, v4, 1
	v_ashrrev_i32_e32 v4, 31, v2
	v_lshrrev_b32_e32 v4, 22, v4
	v_add_u32_e32 v4, v2, v4
	v_ashrrev_i32_e32 v4, 10, v4
	v_lshl_add_u32 v1, v5, 11, v8
	v_mul_i32_i24_e32 v5, 0x400, v4
	v_sub_u32_e32 v2, v2, v5
	s_load_dwordx2 s[14:15], s[66:67], 0x98
	s_nop 0
	s_load_dwordx2 s[66:67], s[8:9], 0x98
	s_load_dwordx2 s[68:69], s[12:13], 0x98
	s_nop 0
	s_load_dwordx2 s[70:71], s[70:71], 0x98
	v_lshrrev_b32_e32 v5, 4, v2
	v_bitop3_b32 v2, v5, v2, 32 bitop3:0x6c
	s_waitcnt lgkmcnt(0)
	s_add_u32 s14, s14, 0x1200000
	v_ashrrev_i32_e32 v9, 31, v2
	s_addc_u32 s15, s15, 0
	v_lshrrev_b32_e32 v9, 26, v9
	s_ashr_i32 s27, s29, 6
	v_lshlrev_b32_e32 v5, 3, v4
	v_add_u32_e32 v10, v2, v9
	s_lshl_b32 s16, s27, 10
	v_and_b32_e32 v5, -16, v5
	s_waitcnt vmcnt(20)
	v_ashrrev_i32_e32 v11, 6, v10
	s_add_i32 s16, s16, 0
	v_add_u32_e32 v9, v11, v5
	v_and_b32_e32 v11, 3, v11
	s_cmp_lt_i32 s6, 36
	v_and_or_b32 v11, v9, s7, v11
	s_cselect_b32 s7, 0, 0xffffffdc
	s_cselect_b32 s9, 0, 4
	s_add_i32 s7, s7, s6
	v_and_b32_e32 v5, 0xc0, v10
	s_and_b32 s6, s36, 3
	s_ashr_i32 s8, s7, 2
	v_sub_u32_e32 v2, v2, v5
	s_or_b32 s6, s6, s9
	s_ashr_i32 s9, s8, 31
	v_lshlrev_b32_e32 v4, 5, v4
	v_ashrrev_i16_sdwa v2, v253, sext(v2) dst_sel:DWORD dst_unused:UNUSED_PAD src0_sel:DWORD src1_sel:BYTE_0
	v_lshlrev_b32_e32 v5, 1, v9
	v_lshrrev_b32_e32 v10, 2, v9
	s_or_b32 s17, s6, s28
	s_lshl_b64 s[6:7], s[8:9], 19
	v_and_b32_e32 v4, 32, v4
	v_bfe_i32 v2, v2, 0, 16
	v_and_b32_e32 v5, 24, v5
	v_and_b32_e32 v10, 4, v10
	s_add_u32 s12, s14, s6
	v_or3_b32 v5, v11, v10, v5
	v_add_lshl_u32 v10, v4, v2, 1
	s_addc_u32 s13, s15, s7
	s_add_i32 m0, s16, 0x10000
	s_nop 0
	global_load_lds_dwordx4 v1, s[12:13]
	v_lshl_add_u32 v134, v5, 11, v10
	s_add_i32 m0, s16, 0x12000
	s_nop 0
	global_load_lds_dwordx4 v134, s[12:13]
	s_add_u32 s6, s12, 0x40000
	s_addc_u32 s7, s13, 0
	s_add_i32 m0, s16, 0x14000
	s_nop 0
	global_load_lds_dwordx4 v1, s[6:7]
	s_nop 0
	s_add_i32 m0, s16, 0x16000
	s_nop 0
	global_load_lds_dwordx4 v134, s[6:7]
	v_readfirstlane_b32 s100, v0
	s_lshr_b32 s100, s100, 6
	s_cmp_lg_u32 s100, 1
	s_cbranch_scc1 .Lpacq1_skip
	buffer_inv sc1
	s_waitcnt vmcnt(0)
.Lpacq1_skip:
	s_and_saveexec_b64 s[72:73], s[4:5]
	s_cbranch_execz .LBB0_377
	v_mov_b32_e32 v2, v0
	s_lshl_b32 s6, s17, 6
	s_bitset1_b32 s6, 14
	v_and_b32_e32 v2, 3, v2
	v_mov_b32_e32 v4, s6
	v_cmp_eq_u32_e32 vcc, 0, v2
	s_nop 1
	v_cndmask_b32_e32 v2, 0, v4, vcc
	v_lshlrev_b32_e32 v2, 2, v2
	global_load_dword v4, v2, s[24:25] sc1
	v_cndmask_b32_e64 v11, 0, 32, vcc
	s_waitcnt vmcnt(0)
	v_cmp_lt_u32_e32 vcc, v4, v11
	s_cbranch_vccz .LBB0_376
	s_memrealtime s[74:75]
	v_lshl_add_u64 v[4:5], s[24:25], 0, v[2:3]
	s_mov_b32 s6, 1
	s_branch .LBB0_332

.LBB0_376:
	s_waitcnt vmcnt(0) lgkmcnt(0)
	s_waitcnt vmcnt(0)

.LBB0_539:
	s_cmp_lg_u32 s42, 6
	s_cselect_b64 s[2:3], -1, 0
	s_cmp_eq_u32 s42, 3
	s_cselect_b32 s51, 0x48, 32
	s_cmp_eq_u32 s42, 6
	s_cselect_b64 s[66:67], -1, 0
	s_and_b64 s[8:9], s[66:67], exec
	s_cselect_b32 s7, 0xb0, s51
	s_add_i32 s6, s6, s36
	s_cmp_ge_i32 s6, s7
	s_mov_b32 s57, 0
	s_cbranch_scc1 .LBB0_879
	s_lshr_b32 s7, s7, 1
	s_cmp_lt_i32 s6, s7
	s_cselect_b64 s[72:73], -1, 0
	s_and_b64 s[8:9], s[72:73], exec
	s_cselect_b32 s8, 0, 4
	s_and_b32 s9, s36, 3
	s_or_b32 s8, s9, s8
	s_or_b32 s44, s8, s28
	s_cmp_lt_u32 s42, 6
	s_cselect_b64 s[70:71], -1, 0
	s_mov_b32 s8, -1
	s_and_b64 vcc, exec, s[70:71]
	s_cbranch_vccnz .LBB0_575
	v_readfirstlane_b32 s100, v0
	s_lshr_b32 s100, s100, 6
	s_cmp_lg_u32 s100, 1
	s_cbranch_scc1 .Lpacq7_skip
	buffer_inv sc1
	s_waitcnt vmcnt(0)
.Lpacq7_skip:
	s_and_saveexec_b64 s[74:75], s[4:5]
	s_cbranch_execz .LBB0_574
	s_lshl_b32 s14, s44, 6
	s_and_b64 vcc, exec, s[2:3]
	s_cbranch_vccz .LBB0_554
	v_mov_b32_e32 v2, v0
	s_or_b32 s8, s14, 0x8000
	v_and_b32_e32 v2, 3, v2
	v_cmp_eq_u32_e32 vcc, 0, v2
	v_cmp_eq_u32_e64 s[2:3], 1, v2
	v_mov_b32_e32 v2, 0x1840
	v_mov_b32_e32 v4, s8
	v_cndmask_b32_e64 v2, 0, v2, s[2:3]
	v_cndmask_b32_e32 v2, v2, v4, vcc
	v_cndmask_b32_e64 v4, 0, v195, s[2:3]
	v_lshlrev_b32_e32 v2, 2, v2
	s_waitcnt vmcnt(27)
	v_cndmask_b32_e32 v6, v4, v194, vcc
	global_load_dword v4, v2, s[24:25] sc1
	s_mov_b64 s[2:3], 0
	s_mov_b64 s[78:79], 0
	s_waitcnt vmcnt(0)
	v_cmp_lt_u32_e32 vcc, v4, v6
	s_cbranch_vccz .LBB0_557
	s_memrealtime s[8:9]
	v_lshl_add_u64 v[4:5], s[24:25], 0, v[2:3]
	s_mov_b32 s15, 1
	s_branch .LBB0_547

.LBB0_573:
	s_or_b64 exec, exec, s[2:3]
	s_waitcnt vmcnt(0) lgkmcnt(0)
	s_waitcnt vmcnt(0)

.LBB0_903:
	s_add_i32 s6, s6, s36
	s_cmp_ge_i32 s6, s7
	s_mov_b32 s57, 0
	s_cbranch_scc1 .LBB0_1210
	s_lshr_b32 s7, s7, 1
	s_cmp_lt_i32 s6, s7
	s_cselect_b64 s[68:69], -1, 0
	s_and_b64 s[16:17], s[68:69], exec
	s_cselect_b32 s15, 0, 4
	s_and_b32 s16, s36, 3
	s_or_b32 s15, s16, s15
	s_or_b32 s19, s15, s28
	s_waitcnt lgkmcnt(0)
	s_add_u32 s20, s8, s2
	s_addc_u32 s36, s9, s3
	s_cmp_lt_u32 s42, 6
	s_cselect_b64 s[66:67], -1, 0
	s_mov_b32 s2, -1
	s_and_b64 vcc, exec, s[66:67]
	s_cbranch_vccnz .LBB0_925
	v_readfirstlane_b32 s100, v0
	s_lshr_b32 s100, s100, 6
	s_cmp_lg_u32 s100, 1
	s_cbranch_scc1 .Lpacq3_skip
	buffer_inv sc1
	s_waitcnt vmcnt(0)
.Lpacq3_skip:
	s_and_saveexec_b64 s[74:75], s[4:5]
	s_cbranch_execz .LBB0_922
	s_lshl_b32 s2, s19, 6
	s_or_b32 s8, s2, 0x7000
	s_add_i32 s2, s19, 1
	s_and_b32 s3, s2, 31
	s_lshl_b32 s2, s2, 6
	v_mov_b32_e32 v1, v0
	s_or_b32 s2, s2, 0x6000
	s_cmp_eq_u32 s3, 0
	v_and_b32_e32 v1, 3, v1
	s_cselect_b32 s2, 0, s2
	v_cmp_eq_u32_e32 vcc, 2, v1
	v_mov_b32_e32 v4, s2
	v_cmp_eq_u32_e64 s[2:3], 1, v1
	v_cndmask_b32_e32 v2, 0, v252, vcc
	s_cselect_b32 s15, 0, 32
	v_cndmask_b32_e64 v2, v2, v4, s[2:3]
	v_mov_b32_e32 v4, s8
	v_cmp_eq_u32_e64 s[8:9], 0, v1
	v_cndmask_b32_e32 v1, 0, v195, vcc
	s_waitcnt vmcnt(24)
	v_mov_b32_e32 v7, s15
	v_cndmask_b32_e64 v2, v2, v4, s[8:9]
	v_lshl_add_u64 v[4:5], v[2:3], 2, s[24:25]
	global_load_dword v2, v[4:5], off sc1
	v_cndmask_b32_e64 v1, v1, v7, s[2:3]
	v_cndmask_b32_e64 v1, v1, 32, s[8:9]
	s_waitcnt vmcnt(0)
	v_cmp_lt_u32_e32 vcc, v2, v1
	s_cbranch_vccz .LBB0_921
	s_memrealtime s[2:3]
	s_mov_b32 s15, 1
	s_branch .LBB0_910
